# ATTN bias-table rebuild de-serialised: a thread's (up to 3) bucket reads and bias loads issued together, one wait each
# baseline (speedup 1.0000x reference)
.LBB0_1279:
	s_lshl_b32 s39, s45, 6
	s_and_b32 s8, s2, 3
	v_or_b32_e32 v130, s39, v154
	s_ashr_i32 s51, s50, 31
	s_lshl_b32 s2, s8, 2
	s_lshl_b64 s[46:47], s[50:51], 11
	v_ashrrev_i32_e32 v131, 31, v130
	s_add_i32 s3, s2, s21
	v_lshl_add_u64 v[0:1], s[46:47], 0, v[130:131]
	v_lshlrev_b64 v[2:3], 11, v[0:1]
	s_lshl_b32 s48, s3, 6
	v_lshl_add_u64 v[2:3], s[56:57], 0, v[2:3]
	s_ashr_i32 s49, s48, 31
	v_lshl_add_u64 v[2:3], s[48:49], 1, v[2:3]
	v_mov_b32_e32 v117, v32
	v_lshl_add_u64 v[2:3], v[2:3], 0, v[116:117]
	global_load_dwordx4 v[80:83], v[2:3], off
	global_load_dwordx4 v[84:87], v[2:3], off offset:32
	global_load_dwordx4 v[88:91], v[2:3], off offset:64
	global_load_dwordx4 v[92:95], v[2:3], off offset:96
	v_mov_b64_e32 v[2:3], s[76:77]
	v_mad_u64_u32 v[2:3], s[0:1], v0, s20, v[2:3]
	s_mul_i32 s0, s3, 3
	v_mad_i32_i24 v3, v1, s20, v3
	s_ashr_i32 s1, s0, 31
	v_lshl_add_u64 v[0:1], s[0:1], 2, v[2:3]
	global_load_dwordx3 v[104:106], v[0:1], off
	s_barrier
	v_readlane_b32 s0, v254, 1
	s_nop 3
	s_cmp_eq_u32 s0, s8
	s_cbranch_scc1 .Lfa_btab_skip
	v_writelane_b32 v254, s8, 1
	s_and_saveexec_b64 s[0:1], s[22:23]
	s_cbranch_execz .LBB0_1284
	v_or_b32_e32 v0, s2, v196
	s_movk_i32 s6, 0xbf
	s_add_i32 s7, s71, 0xffffff00
	v_ashrrev_i32_e32 v4, 2, v107
	v_add_u32_e32 v2, 0x200, v107
	v_ashrrev_i32_e32 v5, 2, v2
	v_add_u32_e32 v2, 0x400, v107
	v_ashrrev_i32_e32 v6, 2, v2
	v_med3_i32 v7, v4, 64, s6
	v_med3_i32 v8, v5, 64, s6
	v_med3_i32 v9, v6, 64, s6
	v_lshl_add_u32 v7, v7, 2, s7
	v_lshl_add_u32 v8, v8, 2, s7
	v_lshl_add_u32 v9, v9, 2, s7
	ds_read_b32 v7, v7
	ds_read_b32 v8, v8
	ds_read_b32 v9, v9
	v_mov_b32_e32 v3, 0xff800000
	s_waitcnt lgkmcnt(0)
	v_lshl_or_b32 v10, v7, 4, v0
	v_lshl_or_b32 v12, v8, 4, v0
	v_lshl_or_b32 v14, v9, 4, v0
	v_ashrrev_i32_e32 v11, 31, v10
	v_ashrrev_i32_e32 v13, 31, v12
	v_ashrrev_i32_e32 v15, 31, v14
	v_lshl_add_u64 v[10:11], v[10:11], 2, s[86:87]
	v_lshl_add_u64 v[12:13], v[12:13], 2, s[86:87]
	v_lshl_add_u64 v[14:15], v[14:15], 2, s[86:87]
	global_load_dword v7, v[10:11], off
	global_load_dword v8, v[12:13], off
	global_load_dword v9, v[14:15], off
	v_cmp_lt_i32_e32 vcc, 63, v4
	s_waitcnt vmcnt(0)
	v_mul_f32_e32 v7, 0x3fb8aa3b, v7
	v_mul_f32_e32 v8, 0x3fb8aa3b, v8
	v_mul_f32_e32 v9, 0x3fb8aa3b, v9
	v_cndmask_b32_e32 v7, v3, v7, vcc
	ds_write_b32 v205, v7
	ds_write_b32 v205, v8 offset:512
	s_movk_i32 s6, 0x140
	v_cmp_gt_i32_e32 vcc, s6, v107
	s_and_saveexec_b64 s[6:7], vcc
	s_cbranch_execz .Lfa_bt_done
	ds_write_b32 v205, v9 offset:1024
.Lfa_bt_done:
	s_or_b64 exec, exec, s[6:7]
.LBB0_1284:
	s_or_b64 exec, exec, s[0:1]
